# same as previous best with the SB unit remap using dead SGPRs (s6/s7) instead of s98/s99
# baseline (speedup 1.0000x reference)
; #define LAS __attribute__((address_space(3)))
; DI void sb_wg_unit(bf16_t* act, int b, int hh, int Qb, LAS unsigned char* lds, volatile LAS unsigned* ctl, int tid, int wid, int lane) {
;     const int r = lane & 31, h = lane >> 5;
;     const int Q = Qb * 256, q0 = Q + 32 * wid, qpos = q0 + r;
;     const size_t rowq = (size_t)b * SEQ + qpos;
;     bf16x8 qf[4]; load_q(qf, act + rowq * PITCH + C_QA + hh * 64, h);
;     f32x16 o0, o1;
; #pragma unroll
;     for (int i = 0; i < 16; ++i) { o0[i] = 0.f; o1[i] = 0.f; }
;     float C = 1.f;
;     const bf16_t* kgb = act + (size_t)b * SEQ * PITCH + C_KA + hh * 64;
;     int t = q0 >> 6;
;     bool done = false;
;     int t_top = (Q >> 6) + 3;
.LBB0_334:
	s_and_b32 s6, s17, 7
	s_lshl_b32 s6, s6, 5
	s_bfe_u32 s7, s17, 0x50003
	s_or_b32 s6, s6, s7
	s_andn2_b32 s7, s17, 0xff
	s_or_b32 s7, s6, s7
	s_lshl_b32 s38, s7, 2
	s_and_b32 s38, s38, 0x380
	s_and_b32 s10, s7, 31
	s_lshl_b32 s21, s10, 8
	s_ashr_i32 s6, s7, 8
	s_add_i32 s21, s21, s16
	v_or_b32_e32 v86, s21, v83
	s_ashr_i32 s7, s6, 31
	s_lshl_b64 s[8:9], s[6:7], 13
	v_ashrrev_i32_e32 v87, 31, v86
	v_lshl_add_u64 v[2:3], s[8:9], 0, v[86:87]
	v_mov_b64_e32 v[4:5], s[76:77]
	v_mad_u64_u32 v[4:5], s[8:9], v2, s31, v[4:5]
	v_mad_i32_i24 v5, v3, s31, v5
	v_lshl_add_u64 v[88:89], v[4:5], 0, s[38:39]
	v_lshl_add_u64 v[84:85], v[88:89], 0, v[0:1]
	global_load_dwordx4 v[66:69], v[84:85], off
	global_load_dwordx4 v[70:73], v[84:85], off offset:32
	global_load_dwordx4 v[74:77], v[84:85], off offset:64
	global_load_dwordx4 v[78:81], v[84:85], off offset:96
	s_mul_hi_i32 s7, s6, 0x6400000
	s_mul_i32 s6, s6, 0x6400000
	s_add_u32 s6, s76, s6
	s_addc_u32 s7, s77, s7
	s_add_u32 s6, s6, s38
	s_addc_u32 s7, s7, 0
	s_lshl_b32 s8, s10, 2
	s_ashr_i32 s24, s21, 6
	s_or_b32 s25, s8, 3
	v_mov_b32_e32 v18, v1
	v_mov_b32_e32 v19, v1
	v_mov_b32_e32 v20, v1
	v_mov_b32_e32 v21, v1
	v_mov_b32_e32 v22, v1
	v_mov_b32_e32 v23, v1
	v_mov_b32_e32 v24, v1
	v_mov_b32_e32 v25, v1
	v_mov_b32_e32 v26, v1
	v_mov_b32_e32 v27, v1
	v_mov_b32_e32 v28, v1
	v_mov_b32_e32 v29, v1
	v_mov_b32_e32 v30, v1
	v_mov_b32_e32 v31, v1
	v_mov_b32_e32 v32, v1
	v_mov_b32_e32 v33, v1
	s_waitcnt lgkmcnt(0)
	v_mov_b64_e32 v[2:3], v[18:19]
	v_mov_b32_e32 v91, 1.0
	s_mov_b64 s[8:9], 0
	v_mov_b64_e32 v[4:5], v[20:21]
	v_mov_b64_e32 v[6:7], v[22:23]
	v_mov_b64_e32 v[8:9], v[24:25]
	v_mov_b64_e32 v[10:11], v[26:27]
	v_mov_b64_e32 v[12:13], v[28:29]
	v_mov_b64_e32 v[14:15], v[30:31]
	v_mov_b64_e32 v[16:17], v[32:33]
	s_branch .LBB0_336
